# GEMM K-loops: drop back-to-back setprio 0/1 pairs, duplicate lgkmcnt waits, s_nop after m0 folded by reorder
# speedup vs baseline: 1.0554x; 1.0045x over previous
; #define PG8_STAGE(bufoff, gbase, voff) do { _Pragma("unroll") for (int _i = 0; _i < 2; ++_i) \
;         __builtin_amdgcn_global_load_lds((const unsigned*)((const char*)(gbase) + (voff)[_i]), (PG8_LAS unsigned*)(lds + (bufoff) + ldsw + _i * 8192), 16, 0, 0); } while (0)
; #define PG8_LDA(dst, b, h) do { _Pragma("unroll") for (int m = 0; m < 4; ++m) _Pragma("unroll") for (int k = 0; k < 2; ++k) dst[m][k] = *(const PG8_LAS bf16x8*)(lds + PG8_SA(b, h) + aoff + m * 2048 + k * 1024); } while (0)
; #define PG8_LDB(dst, b, h) do { _Pragma("unroll") for (int n = 0; n < 2; ++n) _Pragma("unroll") for (int k = 0; k < 2; ++k) dst[n][k] = *(const PG8_LAS bf16x8*)(lds + PG8_SB(b, h) + boff + n * 2048 + k * 1024); } while (0)
; #define PG8_MMA(ai, bj, At, Bt) do { __builtin_amdgcn_s_setprio(1); _Pragma("unroll") for (int m = 0; m < 4; ++m) _Pragma("unroll") for (int n = 0; n < 2; ++n) _Pragma("unroll") for (int k = 0; k < 2; ++k) \
;         acc[ai][bj][m][n] = __builtin_amdgcn_mfma_f32_16x16x32_bf16(Bt[n][k], At[m][k], acc[ai][bj][m][n], 0, 0, 0); __builtin_amdgcn_s_setprio(0); } while (0)
; #define PG8_WAIT_V(n) asm volatile("s_waitcnt vmcnt(" #n ")" ::: "memory")
; #define PG8_WAIT_L(n) asm volatile("s_waitcnt lgkmcnt(" #n ")" ::: "memory")
; #define PG8_BAR __builtin_amdgcn_s_barrier()
; #define PG8_SCHED __builtin_amdgcn_sched_barrier(0)
; template <class Epi, class Sched, bool ALIGN_EPI = false, bool SP2 = false>
; __device__ __forceinline__ void gemm_phase(PG8_LAS unsigned char* lds, const Gemm g, const Sched& S, const Epi& E) {
;     ...
;             PG8_LDB(B0, 0, 0); PG8_LDB(B1, 0, 1); PG8_SCHED; PG8_LDA(At, 0, 0); PG8_STAGE(PG8_SA(1, 1), a1 + hstep, voffA);
;             PG8_WAIT_V(8); PG8_WAIT_L(0); PG8_BAR; PG8_MMA(0, 0, At, B0); PG8_MMA(0, 1, At, B1); PG8_BAR; PG8_SCHED;
;             PG8_LDA(At, 0, 1); PG8_STAGE(PG8_SB(0, 0), b2, voffB); PG8_STAGE(PG8_SB(0, 1), b2 + hstep, voffB); PG8_STAGE(PG8_SA(0, 0), a2, voffA);
;             PG8_WAIT_V(8); PG8_WAIT_L(0); PG8_BAR; PG8_MMA(1, 0, At, B0); PG8_MMA(1, 1, At, B1); PG8_BAR; PG8_SCHED;
.LBB0_114:
	s_add_u32 s20, s8, 0xfffc0080
	s_addc_u32 s21, s9, -1
	s_add_i32 s41, 0, 0x10000
	s_cmp_eq_u32 s40, 12
	s_cselect_b32 s35, s13, s21
	s_cselect_b32 s34, s22, s20
	v_add_u32_e32 v0, s41, v154
	s_cselect_b32 s31, s11, s39
	s_cselect_b32 s30, s23, s38
	s_add_i32 s20, 0, 0x14000
	ds_read_b128 v[158:161], v0
	ds_read_b128 v[162:165], v0 offset:1024
	ds_read_b128 v[166:169], v0 offset:2048
	ds_read_b128 v[170:173], v0 offset:3072
	v_add_u32_e32 v0, s20, v154
	ds_read_b128 v[174:177], v0
	ds_read_b128 v[178:181], v0 offset:1024
	ds_read_b128 v[182:185], v0 offset:2048
	ds_read_b128 v[186:189], v0 offset:3072
	v_lshl_add_u64 v[152:153], s[8:9], 0, v[146:147]
	s_add_i32 m0, s46, 0xc000
	ds_read_b128 v[190:193], v156
	ds_read_b128 v[194:197], v156 offset:1024
	ds_read_b128 v[206:209], v156 offset:2048
	ds_read_b128 v[210:213], v156 offset:3072
	ds_read_b128 v[214:217], v156 offset:4096
	ds_read_b128 v[218:221], v156 offset:5120
	ds_read_b128 v[222:225], v156 offset:6144
	ds_read_b128 v[226:229], v156 offset:7168
	global_load_lds_dwordx4 v[152:153], off
	s_add_i32 m0, s46, 0xe000
	v_lshl_add_u64 v[152:153], s[8:9], 0, v[148:149]
	global_load_lds_dwordx4 v[152:153], off
	s_waitcnt vmcnt(8)
	s_waitcnt lgkmcnt(0)
	s_barrier
	s_setprio 1
	v_mfma_f32_16x16x32_bf16 v[126:129], v[158:161], v[190:193], v[126:129]
	v_mfma_f32_16x16x32_bf16 v[122:125], v[166:169], v[190:193], v[122:125]
	v_mfma_f32_16x16x32_bf16 v[114:117], v[158:161], v[206:209], v[114:117]
	v_mfma_f32_16x16x32_bf16 v[106:109], v[166:169], v[206:209], v[106:109]
	v_mfma_f32_16x16x32_bf16 v[98:101], v[158:161], v[214:217], v[98:101]
	v_mfma_f32_16x16x32_bf16 v[90:93], v[166:169], v[214:217], v[90:93]
	v_mfma_f32_16x16x32_bf16 v[82:85], v[158:161], v[222:225], v[82:85]
	v_mfma_f32_16x16x32_bf16 v[74:77], v[166:169], v[222:225], v[74:77]
	v_mfma_f32_16x16x32_bf16 v[126:129], v[162:165], v[194:197], v[126:129]
	v_mfma_f32_16x16x32_bf16 v[122:125], v[170:173], v[194:197], v[122:125]
	v_mfma_f32_16x16x32_bf16 v[114:117], v[162:165], v[210:213], v[114:117]
	v_mfma_f32_16x16x32_bf16 v[106:109], v[170:173], v[210:213], v[106:109]
	v_mfma_f32_16x16x32_bf16 v[98:101], v[162:165], v[218:221], v[98:101]
	v_mfma_f32_16x16x32_bf16 v[90:93], v[170:173], v[218:221], v[90:93]
	v_mfma_f32_16x16x32_bf16 v[82:85], v[162:165], v[226:229], v[82:85]
	v_mfma_f32_16x16x32_bf16 v[74:77], v[170:173], v[226:229], v[74:77]
	v_mfma_f32_16x16x32_bf16 v[118:121], v[174:177], v[190:193], v[118:121]
	v_mfma_f32_16x16x32_bf16 v[110:113], v[182:185], v[190:193], v[110:113]
	v_mfma_f32_16x16x32_bf16 v[102:105], v[174:177], v[206:209], v[102:105]
	v_mfma_f32_16x16x32_bf16 v[94:97], v[182:185], v[206:209], v[94:97]
	v_mfma_f32_16x16x32_bf16 v[86:89], v[174:177], v[214:217], v[86:89]
	v_mfma_f32_16x16x32_bf16 v[78:81], v[182:185], v[214:217], v[78:81]
	v_mfma_f32_16x16x32_bf16 v[70:73], v[174:177], v[222:225], v[70:73]
	v_mfma_f32_16x16x32_bf16 v[66:69], v[182:185], v[222:225], v[66:69]
	v_mfma_f32_16x16x32_bf16 v[118:121], v[178:181], v[194:197], v[118:121]
	v_mfma_f32_16x16x32_bf16 v[110:113], v[186:189], v[194:197], v[110:113]
	v_mfma_f32_16x16x32_bf16 v[102:105], v[178:181], v[210:213], v[102:105]
	v_mfma_f32_16x16x32_bf16 v[94:97], v[186:189], v[210:213], v[94:97]
	v_mfma_f32_16x16x32_bf16 v[86:89], v[178:181], v[218:221], v[86:89]
	v_mfma_f32_16x16x32_bf16 v[78:81], v[186:189], v[218:221], v[78:81]
	v_mfma_f32_16x16x32_bf16 v[70:73], v[178:181], v[226:229], v[70:73]
	v_mfma_f32_16x16x32_bf16 v[66:69], v[186:189], v[226:229], v[66:69]
	s_setprio 0
	s_barrier
	s_add_i32 s21, s41, s29
	v_lshl_add_u64 v[152:153], s[30:31], 0, v[134:135]
	s_mov_b32 m0, s21
	ds_read_b128 v[190:193], v156 offset:16384
	ds_read_b128 v[194:197], v156 offset:17408
	ds_read_b128 v[206:209], v156 offset:18432
	ds_read_b128 v[210:213], v156 offset:19456
	ds_read_b128 v[214:217], v156 offset:20480
	ds_read_b128 v[218:221], v156 offset:21504
	ds_read_b128 v[222:225], v156 offset:22528
	ds_read_b128 v[226:229], v156 offset:23552
	global_load_lds_dwordx4 v[152:153], off
	s_add_i32 m0, s21, 0x2000
	s_add_u32 s82, s30, 0x40000
	v_lshl_add_u64 v[230:231], s[30:31], 0, v[130:131]
	s_addc_u32 s83, s31, 0
	s_add_i32 s20, s20, s29
	global_load_lds_dwordx4 v[230:231], off
	v_lshl_add_u64 v[242:243], s[82:83], 0, v[134:135]
	s_mov_b32 m0, s20
	v_lshl_add_u64 v[244:245], s[34:35], 0, v[132:133]
	global_load_lds_dwordx4 v[242:243], off
	s_add_i32 m0, s20, 0x2000
	v_lshl_add_u64 v[242:243], s[82:83], 0, v[130:131]
	global_load_lds_dwordx4 v[242:243], off
	s_mov_b32 m0, s46
	v_lshl_add_u64 v[242:243], s[34:35], 0, v[136:137]
	global_load_lds_dwordx4 v[242:243], off
	s_mov_b32 m0, s47
	s_nop 0
	global_load_lds_dwordx4 v[244:245], off
	s_waitcnt vmcnt(8)
	s_waitcnt lgkmcnt(0)
	s_barrier
; #define PG8_STAGE(bufoff, gbase, voff) do { _Pragma("unroll") for (int _i = 0; _i < 2; ++_i) \
;         __builtin_amdgcn_global_load_lds((const unsigned*)((const char*)(gbase) + (voff)[_i]), (PG8_LAS unsigned*)(lds + (bufoff) + ldsw + _i * 8192), 16, 0, 0); } while (0)
; #define PG8_LDA(dst, b, h) do { _Pragma("unroll") for (int m = 0; m < 4; ++m) _Pragma("unroll") for (int k = 0; k < 2; ++k) dst[m][k] = *(const PG8_LAS bf16x8*)(lds + PG8_SA(b, h) + aoff + m * 2048 + k * 1024); } while (0)
; #define PG8_LDB(dst, b, h) do { _Pragma("unroll") for (int n = 0; n < 2; ++n) _Pragma("unroll") for (int k = 0; k < 2; ++k) dst[n][k] = *(const PG8_LAS bf16x8*)(lds + PG8_SB(b, h) + boff + n * 2048 + k * 1024); } while (0)
; #define PG8_MMA(ai, bj, At, Bt) do { __builtin_amdgcn_s_setprio(1); _Pragma("unroll") for (int m = 0; m < 4; ++m) _Pragma("unroll") for (int n = 0; n < 2; ++n) _Pragma("unroll") for (int k = 0; k < 2; ++k) \
;         acc[ai][bj][m][n] = __builtin_amdgcn_mfma_f32_16x16x32_bf16(Bt[n][k], At[m][k], acc[ai][bj][m][n], 0, 0, 0); __builtin_amdgcn_s_setprio(0); } while (0)
; #define PG8_WAIT_V(n) asm volatile("s_waitcnt vmcnt(" #n ")" ::: "memory")
; #define PG8_WAIT_L(n) asm volatile("s_waitcnt lgkmcnt(" #n ")" ::: "memory")
; #define PG8_BAR __builtin_amdgcn_s_barrier()
; #define PG8_SCHED __builtin_amdgcn_sched_barrier(0)
; template <class Epi, class Sched, bool ALIGN_EPI = false, bool SP2 = false>
; __device__ __forceinline__ void gemm_phase(PG8_LAS unsigned char* lds, const Gemm g, const Sched& S, const Epi& E) {
;     ...
;             PG8_WAIT_V(8); PG8_WAIT_L(0); PG8_BAR; PG8_MMA(1, 0, At, B0); PG8_MMA(1, 1, At, B1); PG8_BAR; PG8_SCHED;
;             PG8_LDB(B0, 1, 0); PG8_LDB(B1, 1, 1); PG8_SCHED; PG8_LDA(At, 1, 0); PG8_STAGE(PG8_SA(0, 1), a2 + hstep, voffA);
;             PG8_WAIT_V(8); PG8_WAIT_L(0); PG8_BAR; PG8_MMA(0, 0, At, B0); PG8_MMA(0, 1, At, B1); PG8_BAR; PG8_SCHED;
	s_setprio 1
	v_mfma_f32_16x16x32_bf16 v[62:65], v[158:161], v[190:193], v[62:65]
	v_mfma_f32_16x16x32_bf16 v[58:61], v[166:169], v[190:193], v[58:61]
	v_mfma_f32_16x16x32_bf16 v[50:53], v[158:161], v[206:209], v[50:53]
	v_mfma_f32_16x16x32_bf16 v[42:45], v[166:169], v[206:209], v[42:45]
	v_mfma_f32_16x16x32_bf16 v[34:37], v[158:161], v[214:217], v[34:37]
	v_mfma_f32_16x16x32_bf16 v[26:29], v[166:169], v[214:217], v[26:29]
	v_mfma_f32_16x16x32_bf16 v[18:21], v[158:161], v[222:225], v[18:21]
	v_mfma_f32_16x16x32_bf16 v[10:13], v[166:169], v[222:225], v[10:13]
	v_mfma_f32_16x16x32_bf16 v[62:65], v[162:165], v[194:197], v[62:65]
	v_mfma_f32_16x16x32_bf16 v[58:61], v[170:173], v[194:197], v[58:61]
	v_mfma_f32_16x16x32_bf16 v[50:53], v[162:165], v[210:213], v[50:53]
	v_mfma_f32_16x16x32_bf16 v[42:45], v[170:173], v[210:213], v[42:45]
	v_mfma_f32_16x16x32_bf16 v[34:37], v[162:165], v[218:221], v[34:37]
	v_mfma_f32_16x16x32_bf16 v[26:29], v[170:173], v[218:221], v[26:29]
	v_mfma_f32_16x16x32_bf16 v[18:21], v[162:165], v[226:229], v[18:21]
	v_mfma_f32_16x16x32_bf16 v[10:13], v[170:173], v[226:229], v[10:13]
	v_mfma_f32_16x16x32_bf16 v[54:57], v[174:177], v[190:193], v[54:57]
	v_mfma_f32_16x16x32_bf16 v[46:49], v[182:185], v[190:193], v[46:49]
	v_mfma_f32_16x16x32_bf16 v[38:41], v[174:177], v[206:209], v[38:41]
	v_mfma_f32_16x16x32_bf16 v[30:33], v[182:185], v[206:209], v[30:33]
	v_mfma_f32_16x16x32_bf16 v[22:25], v[174:177], v[214:217], v[22:25]
	v_mfma_f32_16x16x32_bf16 v[14:17], v[182:185], v[214:217], v[14:17]
	v_mfma_f32_16x16x32_bf16 v[6:9], v[174:177], v[222:225], v[6:9]
	v_mfma_f32_16x16x32_bf16 v[2:5], v[182:185], v[222:225], v[2:5]
	v_mfma_f32_16x16x32_bf16 v[54:57], v[178:181], v[194:197], v[54:57]
	v_mfma_f32_16x16x32_bf16 v[46:49], v[186:189], v[194:197], v[46:49]
	v_mfma_f32_16x16x32_bf16 v[38:41], v[178:181], v[210:213], v[38:41]
	v_mfma_f32_16x16x32_bf16 v[30:33], v[186:189], v[210:213], v[30:33]
	v_mfma_f32_16x16x32_bf16 v[22:25], v[178:181], v[218:221], v[22:25]
	v_mfma_f32_16x16x32_bf16 v[14:17], v[186:189], v[218:221], v[14:17]
	v_mfma_f32_16x16x32_bf16 v[6:9], v[178:181], v[226:229], v[6:9]
	v_mfma_f32_16x16x32_bf16 v[2:5], v[186:189], v[226:229], v[2:5]
	s_setprio 0
	s_barrier
	s_add_i32 s20, 0, 0x18000
	v_add_u32_e32 v0, s20, v154
	s_add_i32 s21, 0, 0x1c000
	ds_read_b128 v[158:161], v0
	ds_read_b128 v[162:165], v0 offset:1024
	ds_read_b128 v[166:169], v0 offset:2048
	ds_read_b128 v[170:173], v0 offset:3072
	v_add_u32_e32 v0, s21, v154
	ds_read_b128 v[174:177], v0
	ds_read_b128 v[178:181], v0 offset:1024
	ds_read_b128 v[182:185], v0 offset:2048
	ds_read_b128 v[186:189], v0 offset:3072
	s_add_u32 s34, s34, 0x40000
	s_addc_u32 s35, s35, 0
	s_mov_b32 m0, s52
	v_lshl_add_u64 v[246:247], s[34:35], 0, v[136:137]
	ds_read_b128 v[190:193], v156 offset:32768
	ds_read_b128 v[194:197], v156 offset:33792
	ds_read_b128 v[206:209], v156 offset:34816
	ds_read_b128 v[210:213], v156 offset:35840
	ds_read_b128 v[214:217], v156 offset:36864
	ds_read_b128 v[218:221], v156 offset:37888
	ds_read_b128 v[222:225], v156 offset:38912
	ds_read_b128 v[226:229], v156 offset:39936
	global_load_lds_dwordx4 v[246:247], off
	s_mov_b32 m0, s53
	v_lshl_add_u64 v[246:247], s[34:35], 0, v[132:133]
	global_load_lds_dwordx4 v[246:247], off
	s_waitcnt vmcnt(8)
	s_waitcnt lgkmcnt(0)
	s_barrier
	s_setprio 1
	v_mfma_f32_16x16x32_bf16 v[126:129], v[158:161], v[190:193], v[126:129]
	v_mfma_f32_16x16x32_bf16 v[122:125], v[166:169], v[190:193], v[122:125]
	v_mfma_f32_16x16x32_bf16 v[114:117], v[158:161], v[206:209], v[114:117]
	v_mfma_f32_16x16x32_bf16 v[106:109], v[166:169], v[206:209], v[106:109]
	v_mfma_f32_16x16x32_bf16 v[98:101], v[158:161], v[214:217], v[98:101]
	v_mfma_f32_16x16x32_bf16 v[90:93], v[166:169], v[214:217], v[90:93]
	v_mfma_f32_16x16x32_bf16 v[82:85], v[158:161], v[222:225], v[82:85]
	v_mfma_f32_16x16x32_bf16 v[74:77], v[166:169], v[222:225], v[74:77]
	v_mfma_f32_16x16x32_bf16 v[126:129], v[162:165], v[194:197], v[126:129]
	v_mfma_f32_16x16x32_bf16 v[122:125], v[170:173], v[194:197], v[122:125]
	v_mfma_f32_16x16x32_bf16 v[114:117], v[162:165], v[210:213], v[114:117]
	v_mfma_f32_16x16x32_bf16 v[106:109], v[170:173], v[210:213], v[106:109]
	v_mfma_f32_16x16x32_bf16 v[98:101], v[162:165], v[218:221], v[98:101]
	v_mfma_f32_16x16x32_bf16 v[90:93], v[170:173], v[218:221], v[90:93]
	v_mfma_f32_16x16x32_bf16 v[82:85], v[162:165], v[226:229], v[82:85]
	v_mfma_f32_16x16x32_bf16 v[74:77], v[170:173], v[226:229], v[74:77]
	v_mfma_f32_16x16x32_bf16 v[118:121], v[174:177], v[190:193], v[118:121]
	v_mfma_f32_16x16x32_bf16 v[110:113], v[182:185], v[190:193], v[110:113]
	v_mfma_f32_16x16x32_bf16 v[102:105], v[174:177], v[206:209], v[102:105]
	v_mfma_f32_16x16x32_bf16 v[94:97], v[182:185], v[206:209], v[94:97]
	v_mfma_f32_16x16x32_bf16 v[86:89], v[174:177], v[214:217], v[86:89]
	v_mfma_f32_16x16x32_bf16 v[78:81], v[182:185], v[214:217], v[78:81]
	v_mfma_f32_16x16x32_bf16 v[70:73], v[174:177], v[222:225], v[70:73]
	v_mfma_f32_16x16x32_bf16 v[66:69], v[182:185], v[222:225], v[66:69]
	v_mfma_f32_16x16x32_bf16 v[118:121], v[178:181], v[194:197], v[118:121]
	v_mfma_f32_16x16x32_bf16 v[110:113], v[186:189], v[194:197], v[110:113]
	v_mfma_f32_16x16x32_bf16 v[102:105], v[178:181], v[210:213], v[102:105]
	v_mfma_f32_16x16x32_bf16 v[94:97], v[186:189], v[210:213], v[94:97]
	v_mfma_f32_16x16x32_bf16 v[86:89], v[178:181], v[218:221], v[86:89]
	v_mfma_f32_16x16x32_bf16 v[78:81], v[186:189], v[218:221], v[78:81]
	v_mfma_f32_16x16x32_bf16 v[70:73], v[178:181], v[226:229], v[70:73]
	v_mfma_f32_16x16x32_bf16 v[66:69], v[186:189], v[226:229], v[66:69]
	s_setprio 0
	s_barrier
; #define PG8_STAGE(bufoff, gbase, voff) do { _Pragma("unroll") for (int _i = 0; _i < 2; ++_i) \
;         __builtin_amdgcn_global_load_lds((const unsigned*)((const char*)(gbase) + (voff)[_i]), (PG8_LAS unsigned*)(lds + (bufoff) + ldsw + _i * 8192), 16, 0, 0); } while (0)
; #define PG8_LDA(dst, b, h) do { _Pragma("unroll") for (int m = 0; m < 4; ++m) _Pragma("unroll") for (int k = 0; k < 2; ++k) dst[m][k] = *(const PG8_LAS bf16x8*)(lds + PG8_SA(b, h) + aoff + m * 2048 + k * 1024); } while (0)
; #define PG8_MMA(ai, bj, At, Bt) do { __builtin_amdgcn_s_setprio(1); _Pragma("unroll") for (int m = 0; m < 4; ++m) _Pragma("unroll") for (int n = 0; n < 2; ++n) _Pragma("unroll") for (int k = 0; k < 2; ++k) \
;         acc[ai][bj][m][n] = __builtin_amdgcn_mfma_f32_16x16x32_bf16(Bt[n][k], At[m][k], acc[ai][bj][m][n], 0, 0, 0); __builtin_amdgcn_s_setprio(0); } while (0)
; #define PG8_WAIT_V(n) asm volatile("s_waitcnt vmcnt(" #n ")" ::: "memory")
; #define PG8_WAIT_L(n) asm volatile("s_waitcnt lgkmcnt(" #n ")" ::: "memory")
; #define PG8_BAR __builtin_amdgcn_s_barrier()
; #define PG8_SCHED __builtin_amdgcn_sched_barrier(0)
; template <class Epi, class Sched, bool ALIGN_EPI = false, bool SP2 = false>
; __device__ __forceinline__ void gemm_phase(PG8_LAS unsigned char* lds, const Gemm g, const Sched& S, const Epi& E) {
;     ...
;         for (int t = 0; t < nt; t += 2) {
;             const bool last = (t == nt - 2);
;             const char* a1 = cA + (size_t)(t + 1) * kstep;
;             const char* a2 = last ? nA : cA + (size_t)(t + 2) * kstep; const char* b2 = last ? nB : cB + (size_t)(t + 2) * kstep;
;     ...
;             PG8_LDA(At, 1, 1); PG8_STAGE(PG8_SB(1, 0), b3, voffB); PG8_STAGE(PG8_SB(1, 1), b3 + hstep, voffB); PG8_STAGE(PG8_SA(1, 0), a3, voffA);
;             PG8_WAIT_V(8); PG8_WAIT_L(0); PG8_BAR; PG8_MMA(1, 0, At, B0); PG8_MMA(1, 1, At, B1); PG8_BAR; PG8_SCHED;
	s_add_i32 s20, s20, s29
	v_lshl_add_u64 v[152:153], v[152:153], 0, s[24:25]
	s_mov_b32 m0, s20
	ds_read_b128 v[190:193], v156 offset:49152
	ds_read_b128 v[194:197], v156 offset:50176
	ds_read_b128 v[206:209], v156 offset:51200
	ds_read_b128 v[210:213], v156 offset:52224
	ds_read_b128 v[214:217], v156 offset:53248
	ds_read_b128 v[218:221], v156 offset:54272
	ds_read_b128 v[222:225], v156 offset:55296
	ds_read_b128 v[226:229], v156 offset:56320
	global_load_lds_dwordx4 v[152:153], off
	s_add_i32 m0, s20, 0x2000
	s_add_u32 s30, s30, 0x40080
	v_lshl_add_u64 v[152:153], v[230:231], 0, s[24:25]
	s_addc_u32 s31, s31, 0
	s_add_i32 s20, s21, s29
	global_load_lds_dwordx4 v[152:153], off
	s_mov_b32 m0, s20
	v_lshl_add_u64 v[152:153], s[30:31], 0, v[134:135]
	global_load_lds_dwordx4 v[152:153], off
	s_add_i32 m0, s20, 0x2000
	v_lshl_add_u64 v[152:153], s[30:31], 0, v[130:131]
	global_load_lds_dwordx4 v[152:153], off
	s_mov_b32 m0, s55
	v_lshl_add_u64 v[152:153], v[242:243], 0, s[24:25]
	global_load_lds_dwordx4 v[152:153], off
	s_mov_b32 m0, s57
	v_lshl_add_u64 v[152:153], v[244:245], 0, s[24:25]
	global_load_lds_dwordx4 v[152:153], off
	s_waitcnt vmcnt(8)
	s_waitcnt lgkmcnt(0)
	s_barrier
	s_setprio 1
	v_mfma_f32_16x16x32_bf16 v[62:65], v[158:161], v[190:193], v[62:65]
	v_mfma_f32_16x16x32_bf16 v[58:61], v[166:169], v[190:193], v[58:61]
	v_mfma_f32_16x16x32_bf16 v[50:53], v[158:161], v[206:209], v[50:53]
	v_mfma_f32_16x16x32_bf16 v[42:45], v[166:169], v[206:209], v[42:45]
	v_mfma_f32_16x16x32_bf16 v[34:37], v[158:161], v[214:217], v[34:37]
	v_mfma_f32_16x16x32_bf16 v[26:29], v[166:169], v[214:217], v[26:29]
	v_mfma_f32_16x16x32_bf16 v[18:21], v[158:161], v[222:225], v[18:21]
	v_mfma_f32_16x16x32_bf16 v[10:13], v[166:169], v[222:225], v[10:13]
	v_mfma_f32_16x16x32_bf16 v[62:65], v[162:165], v[194:197], v[62:65]
	v_mfma_f32_16x16x32_bf16 v[58:61], v[170:173], v[194:197], v[58:61]
	v_mfma_f32_16x16x32_bf16 v[50:53], v[162:165], v[210:213], v[50:53]
	v_mfma_f32_16x16x32_bf16 v[42:45], v[170:173], v[210:213], v[42:45]
	v_mfma_f32_16x16x32_bf16 v[34:37], v[162:165], v[218:221], v[34:37]
	v_mfma_f32_16x16x32_bf16 v[26:29], v[170:173], v[218:221], v[26:29]
	v_mfma_f32_16x16x32_bf16 v[18:21], v[162:165], v[226:229], v[18:21]
	v_mfma_f32_16x16x32_bf16 v[10:13], v[170:173], v[226:229], v[10:13]
	v_mfma_f32_16x16x32_bf16 v[54:57], v[174:177], v[190:193], v[54:57]
	v_mfma_f32_16x16x32_bf16 v[46:49], v[182:185], v[190:193], v[46:49]
	v_mfma_f32_16x16x32_bf16 v[38:41], v[174:177], v[206:209], v[38:41]
	v_mfma_f32_16x16x32_bf16 v[30:33], v[182:185], v[206:209], v[30:33]
	v_mfma_f32_16x16x32_bf16 v[22:25], v[174:177], v[214:217], v[22:25]
	v_mfma_f32_16x16x32_bf16 v[14:17], v[182:185], v[214:217], v[14:17]
	v_mfma_f32_16x16x32_bf16 v[6:9], v[174:177], v[222:225], v[6:9]
	v_mfma_f32_16x16x32_bf16 v[2:5], v[182:185], v[222:225], v[2:5]
	v_mfma_f32_16x16x32_bf16 v[54:57], v[178:181], v[194:197], v[54:57]
	v_mfma_f32_16x16x32_bf16 v[46:49], v[186:189], v[194:197], v[46:49]
	v_mfma_f32_16x16x32_bf16 v[38:41], v[178:181], v[210:213], v[38:41]
	v_mfma_f32_16x16x32_bf16 v[30:33], v[186:189], v[210:213], v[30:33]
	v_mfma_f32_16x16x32_bf16 v[22:25], v[178:181], v[218:221], v[22:25]
	v_mfma_f32_16x16x32_bf16 v[14:17], v[186:189], v[218:221], v[14:17]
	v_mfma_f32_16x16x32_bf16 v[6:9], v[178:181], v[226:229], v[6:9]
	v_mfma_f32_16x16x32_bf16 v[2:5], v[186:189], v[226:229], v[2:5]
	s_setprio 0
	s_barrier
	s_add_i32 s40, s40, 2
	s_add_u32 s8, s8, 0x100
	s_addc_u32 s9, s9, 0
	s_add_u32 s38, s38, 0x100
	s_addc_u32 s39, s39, 0
	s_cmp_gt_u32 s40, 13
	s_cbranch_scc0 .LBB0_114
	s_and_b64 vcc, exec, s[6:7]
	s_cbranch_vccz .LBB0_117
	s_barrier

; #define PG8_STAGE(bufoff, gbase, voff) do { _Pragma("unroll") for (int _i = 0; _i < 2; ++_i) \
;         __builtin_amdgcn_global_load_lds((const unsigned*)((const char*)(gbase) + (voff)[_i]), (PG8_LAS unsigned*)(lds + (bufoff) + ldsw + _i * 8192), 16, 0, 0); } while (0)
; #define PG8_LDA(dst, b, h) do { _Pragma("unroll") for (int m = 0; m < 4; ++m) _Pragma("unroll") for (int k = 0; k < 2; ++k) dst[m][k] = *(const PG8_LAS bf16x8*)(lds + PG8_SA(b, h) + aoff + m * 2048 + k * 1024); } while (0)
; #define PG8_LDB(dst, b, h) do { _Pragma("unroll") for (int n = 0; n < 2; ++n) _Pragma("unroll") for (int k = 0; k < 2; ++k) dst[n][k] = *(const PG8_LAS bf16x8*)(lds + PG8_SB(b, h) + boff + n * 2048 + k * 1024); } while (0)
; #define PG8_MMA(ai, bj, At, Bt) do { __builtin_amdgcn_s_setprio(1); _Pragma("unroll") for (int m = 0; m < 4; ++m) _Pragma("unroll") for (int n = 0; n < 2; ++n) _Pragma("unroll") for (int k = 0; k < 2; ++k) \
;         acc[ai][bj][m][n] = __builtin_amdgcn_mfma_f32_16x16x32_bf16(Bt[n][k], At[m][k], acc[ai][bj][m][n], 0, 0, 0); __builtin_amdgcn_s_setprio(0); } while (0)
; #define PG8_WAIT_V(n) asm volatile("s_waitcnt vmcnt(" #n ")" ::: "memory")
; #define PG8_WAIT_L(n) asm volatile("s_waitcnt lgkmcnt(" #n ")" ::: "memory")
; #define PG8_BAR __builtin_amdgcn_s_barrier()
; #define PG8_SCHED __builtin_amdgcn_sched_barrier(0)
; template <class Epi, class Sched, bool ALIGN_EPI = false, bool SP2 = false>
; __device__ __forceinline__ void gemm_phase(PG8_LAS unsigned char* lds, const Gemm g, const Sched& S, const Epi& E) {
;     ...
;             PG8_LDB(B0, 0, 0); PG8_LDB(B1, 0, 1); PG8_SCHED; PG8_LDA(At, 0, 0); PG8_STAGE(PG8_SA(1, 1), a1 + hstep, voffA);
;             PG8_WAIT_V(8); PG8_WAIT_L(0); PG8_BAR; PG8_MMA(0, 0, At, B0); PG8_MMA(0, 1, At, B1); PG8_BAR; PG8_SCHED;
;             PG8_LDA(At, 0, 1); PG8_STAGE(PG8_SB(0, 0), b2, voffB); PG8_STAGE(PG8_SB(0, 1), b2 + hstep, voffB); PG8_STAGE(PG8_SA(0, 0), a2, voffA);
;             PG8_WAIT_V(8); PG8_WAIT_L(0); PG8_BAR; PG8_MMA(1, 0, At, B0); PG8_MMA(1, 1, At, B1); PG8_BAR; PG8_SCHED;
.LBB0_144:
	s_add_u32 s20, s8, 0xfffc0080
	s_addc_u32 s21, s9, -1
	s_add_i32 s80, 0, 0x10000
	s_cmp_eq_u32 s73, 12
	s_cselect_b32 s39, s17, s21
	s_cselect_b32 s38, s40, s20
	v_add_u32_e32 v149, s80, v147
	s_cselect_b32 s35, s13, s72
	s_cselect_b32 s34, s41, s46
	s_add_i32 s20, 0, 0x14000
	ds_read_b128 v[142:145], v149
	ds_read_b128 v[150:153], v149 offset:1024
	ds_read_b128 v[154:157], v149 offset:2048
	ds_read_b128 v[158:161], v149 offset:3072
	v_add_u32_e32 v149, s20, v147
	ds_read_b128 v[162:165], v149
	ds_read_b128 v[166:169], v149 offset:1024
	ds_read_b128 v[170:173], v149 offset:2048
	ds_read_b128 v[174:177], v149 offset:3072
	v_lshl_add_u64 v[218:219], s[8:9], 0, v[138:139]
	s_add_i32 m0, s28, 0xc000
	ds_read_b128 v[178:181], v148
	ds_read_b128 v[182:185], v148 offset:1024
	ds_read_b128 v[186:189], v148 offset:2048
	ds_read_b128 v[190:193], v148 offset:3072
	ds_read_b128 v[194:197], v148 offset:4096
	ds_read_b128 v[206:209], v148 offset:5120
	ds_read_b128 v[210:213], v148 offset:6144
	ds_read_b128 v[214:217], v148 offset:7168
	global_load_lds_dwordx4 v[218:219], off
	s_add_i32 m0, s28, 0xe000
	v_lshl_add_u64 v[218:219], s[8:9], 0, v[140:141]
	global_load_lds_dwordx4 v[218:219], off
	s_waitcnt vmcnt(8)
	s_waitcnt lgkmcnt(0)
	s_barrier
	s_setprio 1
	v_mfma_f32_16x16x32_bf16 v[126:129], v[142:145], v[178:181], v[126:129]
	v_mfma_f32_16x16x32_bf16 v[122:125], v[154:157], v[178:181], v[122:125]
	v_mfma_f32_16x16x32_bf16 v[110:113], v[142:145], v[186:189], v[110:113]
	v_mfma_f32_16x16x32_bf16 v[106:109], v[154:157], v[186:189], v[106:109]
	v_mfma_f32_16x16x32_bf16 v[94:97], v[142:145], v[194:197], v[94:97]
	v_mfma_f32_16x16x32_bf16 v[90:93], v[154:157], v[194:197], v[90:93]
	v_mfma_f32_16x16x32_bf16 v[78:81], v[142:145], v[210:213], v[78:81]
	v_mfma_f32_16x16x32_bf16 v[74:77], v[154:157], v[210:213], v[74:77]
	v_mfma_f32_16x16x32_bf16 v[126:129], v[150:153], v[182:185], v[126:129]
	v_mfma_f32_16x16x32_bf16 v[122:125], v[158:161], v[182:185], v[122:125]
	v_mfma_f32_16x16x32_bf16 v[110:113], v[150:153], v[190:193], v[110:113]
	v_mfma_f32_16x16x32_bf16 v[106:109], v[158:161], v[190:193], v[106:109]
	v_mfma_f32_16x16x32_bf16 v[94:97], v[150:153], v[206:209], v[94:97]
	v_mfma_f32_16x16x32_bf16 v[90:93], v[158:161], v[206:209], v[90:93]
	v_mfma_f32_16x16x32_bf16 v[78:81], v[150:153], v[214:217], v[78:81]
	v_mfma_f32_16x16x32_bf16 v[74:77], v[158:161], v[214:217], v[74:77]
	v_mfma_f32_16x16x32_bf16 v[118:121], v[162:165], v[178:181], v[118:121]
	v_mfma_f32_16x16x32_bf16 v[114:117], v[170:173], v[178:181], v[114:117]
	v_mfma_f32_16x16x32_bf16 v[102:105], v[162:165], v[186:189], v[102:105]
	v_mfma_f32_16x16x32_bf16 v[98:101], v[170:173], v[186:189], v[98:101]
	v_mfma_f32_16x16x32_bf16 v[86:89], v[162:165], v[194:197], v[86:89]
	v_mfma_f32_16x16x32_bf16 v[82:85], v[170:173], v[194:197], v[82:85]
	v_mfma_f32_16x16x32_bf16 v[70:73], v[162:165], v[210:213], v[70:73]
	v_mfma_f32_16x16x32_bf16 v[66:69], v[170:173], v[210:213], v[66:69]
	v_mfma_f32_16x16x32_bf16 v[118:121], v[166:169], v[182:185], v[118:121]
	v_mfma_f32_16x16x32_bf16 v[114:117], v[174:177], v[182:185], v[114:117]
	v_mfma_f32_16x16x32_bf16 v[102:105], v[166:169], v[190:193], v[102:105]
	v_mfma_f32_16x16x32_bf16 v[98:101], v[174:177], v[190:193], v[98:101]
	v_mfma_f32_16x16x32_bf16 v[86:89], v[166:169], v[206:209], v[86:89]
	v_mfma_f32_16x16x32_bf16 v[82:85], v[174:177], v[206:209], v[82:85]
	v_mfma_f32_16x16x32_bf16 v[70:73], v[166:169], v[214:217], v[70:73]
	v_mfma_f32_16x16x32_bf16 v[66:69], v[174:177], v[214:217], v[66:69]
	s_setprio 0
	s_barrier
	s_add_i32 s21, s80, s47
	v_lshl_add_u64 v[218:219], s[34:35], 0, v[0:1]
	s_mov_b32 m0, s21
	ds_read_b128 v[178:181], v148 offset:16384
	ds_read_b128 v[182:185], v148 offset:17408
	ds_read_b128 v[186:189], v148 offset:18432
	ds_read_b128 v[190:193], v148 offset:19456
	ds_read_b128 v[194:197], v148 offset:20480
	ds_read_b128 v[206:209], v148 offset:21504
	ds_read_b128 v[210:213], v148 offset:22528
	ds_read_b128 v[214:217], v148 offset:23552
	global_load_lds_dwordx4 v[218:219], off
	s_add_i32 m0, s21, 0x2000
	s_add_u32 s82, s34, 0x40000
	v_lshl_add_u64 v[220:221], s[34:35], 0, v[130:131]
	s_addc_u32 s83, s35, 0
	s_add_i32 s20, s20, s47
	global_load_lds_dwordx4 v[220:221], off
	v_lshl_add_u64 v[222:223], s[82:83], 0, v[0:1]
	s_mov_b32 m0, s20
	v_lshl_add_u64 v[224:225], s[38:39], 0, v[132:133]
	global_load_lds_dwordx4 v[222:223], off
	s_add_i32 m0, s20, 0x2000
	v_lshl_add_u64 v[222:223], s[82:83], 0, v[130:131]
	global_load_lds_dwordx4 v[222:223], off
	s_mov_b32 m0, s28
	v_lshl_add_u64 v[222:223], s[38:39], 0, v[134:135]
	global_load_lds_dwordx4 v[222:223], off
	s_mov_b32 m0, s29
	s_nop 0
	global_load_lds_dwordx4 v[224:225], off
	s_waitcnt vmcnt(8)
	s_waitcnt lgkmcnt(0)
	s_barrier
; #define PG8_STAGE(bufoff, gbase, voff) do { _Pragma("unroll") for (int _i = 0; _i < 2; ++_i) \
;         __builtin_amdgcn_global_load_lds((const unsigned*)((const char*)(gbase) + (voff)[_i]), (PG8_LAS unsigned*)(lds + (bufoff) + ldsw + _i * 8192), 16, 0, 0); } while (0)
; #define PG8_LDA(dst, b, h) do { _Pragma("unroll") for (int m = 0; m < 4; ++m) _Pragma("unroll") for (int k = 0; k < 2; ++k) dst[m][k] = *(const PG8_LAS bf16x8*)(lds + PG8_SA(b, h) + aoff + m * 2048 + k * 1024); } while (0)
; #define PG8_LDB(dst, b, h) do { _Pragma("unroll") for (int n = 0; n < 2; ++n) _Pragma("unroll") for (int k = 0; k < 2; ++k) dst[n][k] = *(const PG8_LAS bf16x8*)(lds + PG8_SB(b, h) + boff + n * 2048 + k * 1024); } while (0)
; #define PG8_MMA(ai, bj, At, Bt) do { __builtin_amdgcn_s_setprio(1); _Pragma("unroll") for (int m = 0; m < 4; ++m) _Pragma("unroll") for (int n = 0; n < 2; ++n) _Pragma("unroll") for (int k = 0; k < 2; ++k) \
;         acc[ai][bj][m][n] = __builtin_amdgcn_mfma_f32_16x16x32_bf16(Bt[n][k], At[m][k], acc[ai][bj][m][n], 0, 0, 0); __builtin_amdgcn_s_setprio(0); } while (0)
; #define PG8_WAIT_V(n) asm volatile("s_waitcnt vmcnt(" #n ")" ::: "memory")
; #define PG8_WAIT_L(n) asm volatile("s_waitcnt lgkmcnt(" #n ")" ::: "memory")
; #define PG8_BAR __builtin_amdgcn_s_barrier()
; #define PG8_SCHED __builtin_amdgcn_sched_barrier(0)
; template <class Epi, class Sched, bool ALIGN_EPI = false, bool SP2 = false>
; __device__ __forceinline__ void gemm_phase(PG8_LAS unsigned char* lds, const Gemm g, const Sched& S, const Epi& E) {
;     ...
;             PG8_WAIT_V(8); PG8_WAIT_L(0); PG8_BAR; PG8_MMA(1, 0, At, B0); PG8_MMA(1, 1, At, B1); PG8_BAR; PG8_SCHED;
;             PG8_LDB(B0, 1, 0); PG8_LDB(B1, 1, 1); PG8_SCHED; PG8_LDA(At, 1, 0); PG8_STAGE(PG8_SA(0, 1), a2 + hstep, voffA);
;             PG8_WAIT_V(8); PG8_WAIT_L(0); PG8_BAR; PG8_MMA(0, 0, At, B0); PG8_MMA(0, 1, At, B1); PG8_BAR; PG8_SCHED;
	s_setprio 1
	v_mfma_f32_16x16x32_bf16 v[62:65], v[142:145], v[178:181], v[62:65]
	v_mfma_f32_16x16x32_bf16 v[58:61], v[154:157], v[178:181], v[58:61]
	v_mfma_f32_16x16x32_bf16 v[46:49], v[142:145], v[186:189], v[46:49]
	v_mfma_f32_16x16x32_bf16 v[42:45], v[154:157], v[186:189], v[42:45]
	v_mfma_f32_16x16x32_bf16 v[30:33], v[142:145], v[194:197], v[30:33]
	v_mfma_f32_16x16x32_bf16 v[26:29], v[154:157], v[194:197], v[26:29]
	v_mfma_f32_16x16x32_bf16 v[14:17], v[142:145], v[210:213], v[14:17]
	v_mfma_f32_16x16x32_bf16 v[10:13], v[154:157], v[210:213], v[10:13]
	v_mfma_f32_16x16x32_bf16 v[62:65], v[150:153], v[182:185], v[62:65]
	v_mfma_f32_16x16x32_bf16 v[58:61], v[158:161], v[182:185], v[58:61]
	v_mfma_f32_16x16x32_bf16 v[46:49], v[150:153], v[190:193], v[46:49]
	v_mfma_f32_16x16x32_bf16 v[42:45], v[158:161], v[190:193], v[42:45]
	v_mfma_f32_16x16x32_bf16 v[30:33], v[150:153], v[206:209], v[30:33]
	v_mfma_f32_16x16x32_bf16 v[26:29], v[158:161], v[206:209], v[26:29]
	v_mfma_f32_16x16x32_bf16 v[14:17], v[150:153], v[214:217], v[14:17]
	v_mfma_f32_16x16x32_bf16 v[10:13], v[158:161], v[214:217], v[10:13]
	v_mfma_f32_16x16x32_bf16 v[54:57], v[162:165], v[178:181], v[54:57]
	v_mfma_f32_16x16x32_bf16 v[50:53], v[170:173], v[178:181], v[50:53]
	v_mfma_f32_16x16x32_bf16 v[38:41], v[162:165], v[186:189], v[38:41]
	v_mfma_f32_16x16x32_bf16 v[34:37], v[170:173], v[186:189], v[34:37]
	v_mfma_f32_16x16x32_bf16 v[22:25], v[162:165], v[194:197], v[22:25]
	v_mfma_f32_16x16x32_bf16 v[18:21], v[170:173], v[194:197], v[18:21]
	v_mfma_f32_16x16x32_bf16 v[6:9], v[162:165], v[210:213], v[6:9]
	v_mfma_f32_16x16x32_bf16 v[2:5], v[170:173], v[210:213], v[2:5]
	v_mfma_f32_16x16x32_bf16 v[54:57], v[166:169], v[182:185], v[54:57]
	v_mfma_f32_16x16x32_bf16 v[50:53], v[174:177], v[182:185], v[50:53]
	v_mfma_f32_16x16x32_bf16 v[38:41], v[166:169], v[190:193], v[38:41]
	v_mfma_f32_16x16x32_bf16 v[34:37], v[174:177], v[190:193], v[34:37]
	v_mfma_f32_16x16x32_bf16 v[22:25], v[166:169], v[206:209], v[22:25]
	v_mfma_f32_16x16x32_bf16 v[18:21], v[174:177], v[206:209], v[18:21]
	v_mfma_f32_16x16x32_bf16 v[6:9], v[166:169], v[214:217], v[6:9]
	v_mfma_f32_16x16x32_bf16 v[2:5], v[174:177], v[214:217], v[2:5]
	s_setprio 0
	s_barrier
	s_add_i32 s20, 0, 0x18000
	v_add_u32_e32 v149, s20, v147
	s_add_i32 s21, 0, 0x1c000
	ds_read_b128 v[142:145], v149
	ds_read_b128 v[150:153], v149 offset:1024
	ds_read_b128 v[154:157], v149 offset:2048
	ds_read_b128 v[158:161], v149 offset:3072
	v_add_u32_e32 v149, s21, v147
	ds_read_b128 v[162:165], v149
	ds_read_b128 v[166:169], v149 offset:1024
	ds_read_b128 v[170:173], v149 offset:2048
	ds_read_b128 v[174:177], v149 offset:3072
	s_add_u32 s38, s38, 0x40000
	s_addc_u32 s39, s39, 0
	s_mov_b32 m0, s52
	v_lshl_add_u64 v[226:227], s[38:39], 0, v[134:135]
	ds_read_b128 v[178:181], v148 offset:32768
	ds_read_b128 v[182:185], v148 offset:33792
	ds_read_b128 v[186:189], v148 offset:34816
	ds_read_b128 v[190:193], v148 offset:35840
	ds_read_b128 v[194:197], v148 offset:36864
	ds_read_b128 v[206:209], v148 offset:37888
	ds_read_b128 v[210:213], v148 offset:38912
	ds_read_b128 v[214:217], v148 offset:39936
	global_load_lds_dwordx4 v[226:227], off
	s_mov_b32 m0, s53
	v_lshl_add_u64 v[226:227], s[38:39], 0, v[132:133]
	global_load_lds_dwordx4 v[226:227], off
	s_waitcnt vmcnt(8)
	s_waitcnt lgkmcnt(0)
	s_barrier
	s_setprio 1
	v_mfma_f32_16x16x32_bf16 v[126:129], v[142:145], v[178:181], v[126:129]
	v_mfma_f32_16x16x32_bf16 v[122:125], v[154:157], v[178:181], v[122:125]
	v_mfma_f32_16x16x32_bf16 v[110:113], v[142:145], v[186:189], v[110:113]
	v_mfma_f32_16x16x32_bf16 v[106:109], v[154:157], v[186:189], v[106:109]
	v_mfma_f32_16x16x32_bf16 v[94:97], v[142:145], v[194:197], v[94:97]
	v_mfma_f32_16x16x32_bf16 v[90:93], v[154:157], v[194:197], v[90:93]
	v_mfma_f32_16x16x32_bf16 v[78:81], v[142:145], v[210:213], v[78:81]
	v_mfma_f32_16x16x32_bf16 v[74:77], v[154:157], v[210:213], v[74:77]
	v_mfma_f32_16x16x32_bf16 v[126:129], v[150:153], v[182:185], v[126:129]
	v_mfma_f32_16x16x32_bf16 v[122:125], v[158:161], v[182:185], v[122:125]
	v_mfma_f32_16x16x32_bf16 v[110:113], v[150:153], v[190:193], v[110:113]
	v_mfma_f32_16x16x32_bf16 v[106:109], v[158:161], v[190:193], v[106:109]
	v_mfma_f32_16x16x32_bf16 v[94:97], v[150:153], v[206:209], v[94:97]
	v_mfma_f32_16x16x32_bf16 v[90:93], v[158:161], v[206:209], v[90:93]
	v_mfma_f32_16x16x32_bf16 v[78:81], v[150:153], v[214:217], v[78:81]
	v_mfma_f32_16x16x32_bf16 v[74:77], v[158:161], v[214:217], v[74:77]
	v_mfma_f32_16x16x32_bf16 v[118:121], v[162:165], v[178:181], v[118:121]
	v_mfma_f32_16x16x32_bf16 v[114:117], v[170:173], v[178:181], v[114:117]
	v_mfma_f32_16x16x32_bf16 v[102:105], v[162:165], v[186:189], v[102:105]
	v_mfma_f32_16x16x32_bf16 v[98:101], v[170:173], v[186:189], v[98:101]
	v_mfma_f32_16x16x32_bf16 v[86:89], v[162:165], v[194:197], v[86:89]
	v_mfma_f32_16x16x32_bf16 v[82:85], v[170:173], v[194:197], v[82:85]
	v_mfma_f32_16x16x32_bf16 v[70:73], v[162:165], v[210:213], v[70:73]
	v_mfma_f32_16x16x32_bf16 v[66:69], v[170:173], v[210:213], v[66:69]
	v_mfma_f32_16x16x32_bf16 v[118:121], v[166:169], v[182:185], v[118:121]
	v_mfma_f32_16x16x32_bf16 v[114:117], v[174:177], v[182:185], v[114:117]
	v_mfma_f32_16x16x32_bf16 v[102:105], v[166:169], v[190:193], v[102:105]
	v_mfma_f32_16x16x32_bf16 v[98:101], v[174:177], v[190:193], v[98:101]
	v_mfma_f32_16x16x32_bf16 v[86:89], v[166:169], v[206:209], v[86:89]
	v_mfma_f32_16x16x32_bf16 v[82:85], v[174:177], v[206:209], v[82:85]
	v_mfma_f32_16x16x32_bf16 v[70:73], v[166:169], v[214:217], v[70:73]
	v_mfma_f32_16x16x32_bf16 v[66:69], v[174:177], v[214:217], v[66:69]
	s_setprio 0
	s_barrier
; #define PG8_STAGE(bufoff, gbase, voff) do { _Pragma("unroll") for (int _i = 0; _i < 2; ++_i) \
;         __builtin_amdgcn_global_load_lds((const unsigned*)((const char*)(gbase) + (voff)[_i]), (PG8_LAS unsigned*)(lds + (bufoff) + ldsw + _i * 8192), 16, 0, 0); } while (0)
; #define PG8_LDA(dst, b, h) do { _Pragma("unroll") for (int m = 0; m < 4; ++m) _Pragma("unroll") for (int k = 0; k < 2; ++k) dst[m][k] = *(const PG8_LAS bf16x8*)(lds + PG8_SA(b, h) + aoff + m * 2048 + k * 1024); } while (0)
; #define PG8_MMA(ai, bj, At, Bt) do { __builtin_amdgcn_s_setprio(1); _Pragma("unroll") for (int m = 0; m < 4; ++m) _Pragma("unroll") for (int n = 0; n < 2; ++n) _Pragma("unroll") for (int k = 0; k < 2; ++k) \
;         acc[ai][bj][m][n] = __builtin_amdgcn_mfma_f32_16x16x32_bf16(Bt[n][k], At[m][k], acc[ai][bj][m][n], 0, 0, 0); __builtin_amdgcn_s_setprio(0); } while (0)
; #define PG8_WAIT_V(n) asm volatile("s_waitcnt vmcnt(" #n ")" ::: "memory")
; #define PG8_WAIT_L(n) asm volatile("s_waitcnt lgkmcnt(" #n ")" ::: "memory")
; #define PG8_BAR __builtin_amdgcn_s_barrier()
; #define PG8_SCHED __builtin_amdgcn_sched_barrier(0)
; template <class Epi, class Sched, bool ALIGN_EPI = false, bool SP2 = false>
; __device__ __forceinline__ void gemm_phase(PG8_LAS unsigned char* lds, const Gemm g, const Sched& S, const Epi& E) {
;     ...
;         for (int t = 0; t < nt; t += 2) {
;             const bool last = (t == nt - 2);
;             const char* a1 = cA + (size_t)(t + 1) * kstep;
;             const char* a2 = last ? nA : cA + (size_t)(t + 2) * kstep; const char* b2 = last ? nB : cB + (size_t)(t + 2) * kstep;
;     ...
;             PG8_LDA(At, 1, 1); PG8_STAGE(PG8_SB(1, 0), b3, voffB); PG8_STAGE(PG8_SB(1, 1), b3 + hstep, voffB); PG8_STAGE(PG8_SA(1, 0), a3, voffA);
;             PG8_WAIT_V(8); PG8_WAIT_L(0); PG8_BAR; PG8_MMA(1, 0, At, B0); PG8_MMA(1, 1, At, B1); PG8_BAR; PG8_SCHED;
	s_add_i32 s20, s20, s47
	v_lshl_add_u64 v[218:219], v[218:219], 0, s[24:25]
	s_mov_b32 m0, s20
	ds_read_b128 v[178:181], v148 offset:49152
	ds_read_b128 v[182:185], v148 offset:50176
	ds_read_b128 v[186:189], v148 offset:51200
	ds_read_b128 v[190:193], v148 offset:52224
	ds_read_b128 v[194:197], v148 offset:53248
	ds_read_b128 v[206:209], v148 offset:54272
	ds_read_b128 v[210:213], v148 offset:55296
	ds_read_b128 v[214:217], v148 offset:56320
	global_load_lds_dwordx4 v[218:219], off
	s_add_i32 m0, s20, 0x2000
	s_add_u32 s34, s34, 0x40080
	v_lshl_add_u64 v[218:219], v[220:221], 0, s[24:25]
	s_addc_u32 s35, s35, 0
	s_add_i32 s20, s21, s47
	global_load_lds_dwordx4 v[218:219], off
	s_mov_b32 m0, s20
	v_lshl_add_u64 v[218:219], s[34:35], 0, v[0:1]
	global_load_lds_dwordx4 v[218:219], off
	s_add_i32 m0, s20, 0x2000
	v_lshl_add_u64 v[218:219], s[34:35], 0, v[130:131]
	global_load_lds_dwordx4 v[218:219], off
	s_mov_b32 m0, s55
	v_lshl_add_u64 v[218:219], v[222:223], 0, s[24:25]
	global_load_lds_dwordx4 v[218:219], off
	s_mov_b32 m0, s57
	v_lshl_add_u64 v[218:219], v[224:225], 0, s[24:25]
	global_load_lds_dwordx4 v[218:219], off
	s_waitcnt vmcnt(8)
	s_waitcnt lgkmcnt(0)
	s_barrier
	s_setprio 1
	v_mfma_f32_16x16x32_bf16 v[62:65], v[142:145], v[178:181], v[62:65]
	v_mfma_f32_16x16x32_bf16 v[58:61], v[154:157], v[178:181], v[58:61]
	v_mfma_f32_16x16x32_bf16 v[46:49], v[142:145], v[186:189], v[46:49]
	v_mfma_f32_16x16x32_bf16 v[42:45], v[154:157], v[186:189], v[42:45]
	v_mfma_f32_16x16x32_bf16 v[30:33], v[142:145], v[194:197], v[30:33]
	v_mfma_f32_16x16x32_bf16 v[26:29], v[154:157], v[194:197], v[26:29]
	v_mfma_f32_16x16x32_bf16 v[14:17], v[142:145], v[210:213], v[14:17]
	v_mfma_f32_16x16x32_bf16 v[10:13], v[154:157], v[210:213], v[10:13]
	v_mfma_f32_16x16x32_bf16 v[62:65], v[150:153], v[182:185], v[62:65]
	v_mfma_f32_16x16x32_bf16 v[58:61], v[158:161], v[182:185], v[58:61]
	v_mfma_f32_16x16x32_bf16 v[46:49], v[150:153], v[190:193], v[46:49]
	v_mfma_f32_16x16x32_bf16 v[42:45], v[158:161], v[190:193], v[42:45]
	v_mfma_f32_16x16x32_bf16 v[30:33], v[150:153], v[206:209], v[30:33]
	v_mfma_f32_16x16x32_bf16 v[26:29], v[158:161], v[206:209], v[26:29]
	v_mfma_f32_16x16x32_bf16 v[14:17], v[150:153], v[214:217], v[14:17]
	v_mfma_f32_16x16x32_bf16 v[10:13], v[158:161], v[214:217], v[10:13]
	v_mfma_f32_16x16x32_bf16 v[54:57], v[162:165], v[178:181], v[54:57]
	v_mfma_f32_16x16x32_bf16 v[50:53], v[170:173], v[178:181], v[50:53]
	v_mfma_f32_16x16x32_bf16 v[38:41], v[162:165], v[186:189], v[38:41]
	v_mfma_f32_16x16x32_bf16 v[34:37], v[170:173], v[186:189], v[34:37]
	v_mfma_f32_16x16x32_bf16 v[22:25], v[162:165], v[194:197], v[22:25]
	v_mfma_f32_16x16x32_bf16 v[18:21], v[170:173], v[194:197], v[18:21]
	v_mfma_f32_16x16x32_bf16 v[6:9], v[162:165], v[210:213], v[6:9]
	v_mfma_f32_16x16x32_bf16 v[2:5], v[170:173], v[210:213], v[2:5]
	v_mfma_f32_16x16x32_bf16 v[54:57], v[166:169], v[182:185], v[54:57]
	v_mfma_f32_16x16x32_bf16 v[50:53], v[174:177], v[182:185], v[50:53]
	v_mfma_f32_16x16x32_bf16 v[38:41], v[166:169], v[190:193], v[38:41]
	v_mfma_f32_16x16x32_bf16 v[34:37], v[174:177], v[190:193], v[34:37]
	v_mfma_f32_16x16x32_bf16 v[22:25], v[166:169], v[206:209], v[22:25]
	v_mfma_f32_16x16x32_bf16 v[18:21], v[174:177], v[206:209], v[18:21]
	v_mfma_f32_16x16x32_bf16 v[6:9], v[166:169], v[214:217], v[6:9]
	v_mfma_f32_16x16x32_bf16 v[2:5], v[174:177], v[214:217], v[2:5]
	s_setprio 0
	s_barrier
	s_add_i32 s73, s73, 2
	s_add_u32 s8, s8, 0x100
	s_addc_u32 s9, s9, 0
	s_add_u32 s46, s46, 0x100
	s_addc_u32 s72, s72, 0
	s_cmp_gt_u32 s73, 13
	s_cbranch_scc0 .LBB0_144
	s_and_b64 vcc, exec, s[6:7]
	s_cbranch_vccz .LBB0_147
	s_barrier

; #define PG8_STAGE(bufoff, gbase, voff) do { _Pragma("unroll") for (int _i = 0; _i < 2; ++_i) \
;         __builtin_amdgcn_global_load_lds((const unsigned*)((const char*)(gbase) + (voff)[_i]), (PG8_LAS unsigned*)(lds + (bufoff) + ldsw + _i * 8192), 16, 0, 0); } while (0)
; #define PG8_LDA(dst, b, h) do { _Pragma("unroll") for (int m = 0; m < 4; ++m) _Pragma("unroll") for (int k = 0; k < 2; ++k) dst[m][k] = *(const PG8_LAS bf16x8*)(lds + PG8_SA(b, h) + aoff + m * 2048 + k * 1024); } while (0)
; #define PG8_LDB(dst, b, h) do { _Pragma("unroll") for (int n = 0; n < 2; ++n) _Pragma("unroll") for (int k = 0; k < 2; ++k) dst[n][k] = *(const PG8_LAS bf16x8*)(lds + PG8_SB(b, h) + boff + n * 2048 + k * 1024); } while (0)
; #define PG8_MMA(ai, bj, At, Bt) do { __builtin_amdgcn_s_setprio(1); _Pragma("unroll") for (int m = 0; m < 4; ++m) _Pragma("unroll") for (int n = 0; n < 2; ++n) _Pragma("unroll") for (int k = 0; k < 2; ++k) \
;         acc[ai][bj][m][n] = __builtin_amdgcn_mfma_f32_16x16x32_bf16(Bt[n][k], At[m][k], acc[ai][bj][m][n], 0, 0, 0); __builtin_amdgcn_s_setprio(0); } while (0)
; #define PG8_WAIT_V(n) asm volatile("s_waitcnt vmcnt(" #n ")" ::: "memory")
; #define PG8_WAIT_L(n) asm volatile("s_waitcnt lgkmcnt(" #n ")" ::: "memory")
; #define PG8_BAR __builtin_amdgcn_s_barrier()
; #define PG8_SCHED __builtin_amdgcn_sched_barrier(0)
; template <class Epi, class Sched, bool ALIGN_EPI = false, bool SP2 = false>
; __device__ __forceinline__ void gemm_phase(PG8_LAS unsigned char* lds, const Gemm g, const Sched& S, const Epi& E) {
;     ...
;             PG8_LDB(B0, 0, 0); PG8_LDB(B1, 0, 1); PG8_SCHED; PG8_LDA(At, 0, 0); PG8_STAGE(PG8_SA(1, 1), a1 + hstep, voffA);
;             PG8_WAIT_V(8); PG8_WAIT_L(0); PG8_BAR; PG8_MMA(0, 0, At, B0); PG8_MMA(0, 1, At, B1); PG8_BAR; PG8_SCHED;
;             PG8_LDA(At, 0, 1); PG8_STAGE(PG8_SB(0, 0), b2, voffB); PG8_STAGE(PG8_SB(0, 1), b2 + hstep, voffB); PG8_STAGE(PG8_SA(0, 0), a2, voffA);
;             PG8_WAIT_V(8); PG8_WAIT_L(0); PG8_BAR; PG8_MMA(1, 0, At, B0); PG8_MMA(1, 1, At, B1); PG8_BAR; PG8_SCHED;
.LBB0_351:
	s_add_u32 s20, s8, 0xfffc0080
	s_addc_u32 s21, s9, -1
	s_add_i32 s80, 0, 0x10000
	s_cmp_eq_u32 s73, 12
	s_cselect_b32 s35, s17, s21
	s_cselect_b32 s34, s40, s20
	s_cselect_b32 s31, s13, s72
	s_cselect_b32 s30, s41, s58
	s_add_i32 s81, 0, 0x14000
	v_add_u32_e32 v148, s80, v153
	v_add_u32_e32 v168, s81, v153
	ds_read_b128 v[130:133], v148
	ds_read_b128 v[134:137], v148 offset:1024
	ds_read_b128 v[138:141], v148 offset:2048
	ds_read_b128 v[148:151], v148 offset:3072
	ds_read_b128 v[156:159], v168
	ds_read_b128 v[160:163], v168 offset:1024
	ds_read_b128 v[164:167], v168 offset:2048
	ds_read_b128 v[168:171], v168 offset:3072
	v_lshl_add_u64 v[196:197], s[8:9], 0, v[144:145]
	s_add_i32 m0, s43, 0xc000
	ds_read_b128 v[172:175], v155
	ds_read_b128 v[176:179], v155 offset:1024
	ds_read_b128 v[180:183], v155 offset:2048
	ds_read_b128 v[184:187], v155 offset:3072
	ds_read_b128 v[188:191], v155 offset:4096
	ds_read_b128 v[192:195], v155 offset:5120
	ds_read_b128 v[206:209], v155 offset:6144
	ds_read_b128 v[210:213], v155 offset:7168
	global_load_lds_dwordx4 v[196:197], off
	s_add_i32 m0, s43, 0xe000
	v_lshl_add_u64 v[196:197], s[8:9], 0, v[146:147]
	global_load_lds_dwordx4 v[196:197], off
	s_waitcnt vmcnt(8)
	s_waitcnt lgkmcnt(0)
	s_barrier
	s_setprio 1
	v_mfma_f32_16x16x32_bf16 v[126:129], v[130:133], v[172:175], v[126:129]
	v_mfma_f32_16x16x32_bf16 v[122:125], v[138:141], v[172:175], v[122:125]
	v_mfma_f32_16x16x32_bf16 v[118:121], v[130:133], v[180:183], v[118:121]
	v_mfma_f32_16x16x32_bf16 v[106:109], v[138:141], v[180:183], v[106:109]
	v_mfma_f32_16x16x32_bf16 v[102:105], v[130:133], v[188:191], v[102:105]
	v_mfma_f32_16x16x32_bf16 v[90:93], v[138:141], v[188:191], v[90:93]
	v_mfma_f32_16x16x32_bf16 v[86:89], v[130:133], v[206:209], v[86:89]
	v_mfma_f32_16x16x32_bf16 v[74:77], v[138:141], v[206:209], v[74:77]
	v_mfma_f32_16x16x32_bf16 v[126:129], v[134:137], v[176:179], v[126:129]
	v_mfma_f32_16x16x32_bf16 v[122:125], v[148:151], v[176:179], v[122:125]
	v_mfma_f32_16x16x32_bf16 v[118:121], v[134:137], v[184:187], v[118:121]
	v_mfma_f32_16x16x32_bf16 v[106:109], v[148:151], v[184:187], v[106:109]
	v_mfma_f32_16x16x32_bf16 v[102:105], v[134:137], v[192:195], v[102:105]
	v_mfma_f32_16x16x32_bf16 v[90:93], v[148:151], v[192:195], v[90:93]
	v_mfma_f32_16x16x32_bf16 v[86:89], v[134:137], v[210:213], v[86:89]
	v_mfma_f32_16x16x32_bf16 v[74:77], v[148:151], v[210:213], v[74:77]
	v_mfma_f32_16x16x32_bf16 v[114:117], v[156:159], v[172:175], v[114:117]
	v_mfma_f32_16x16x32_bf16 v[110:113], v[164:167], v[172:175], v[110:113]
	v_mfma_f32_16x16x32_bf16 v[98:101], v[156:159], v[180:183], v[98:101]
	v_mfma_f32_16x16x32_bf16 v[94:97], v[164:167], v[180:183], v[94:97]
	v_mfma_f32_16x16x32_bf16 v[82:85], v[156:159], v[188:191], v[82:85]
	v_mfma_f32_16x16x32_bf16 v[78:81], v[164:167], v[188:191], v[78:81]
	v_mfma_f32_16x16x32_bf16 v[70:73], v[156:159], v[206:209], v[70:73]
	v_mfma_f32_16x16x32_bf16 v[66:69], v[164:167], v[206:209], v[66:69]
	v_mfma_f32_16x16x32_bf16 v[114:117], v[160:163], v[176:179], v[114:117]
	v_mfma_f32_16x16x32_bf16 v[110:113], v[168:171], v[176:179], v[110:113]
	v_mfma_f32_16x16x32_bf16 v[98:101], v[160:163], v[184:187], v[98:101]
	v_mfma_f32_16x16x32_bf16 v[94:97], v[168:171], v[184:187], v[94:97]
	v_mfma_f32_16x16x32_bf16 v[82:85], v[160:163], v[192:195], v[82:85]
	v_mfma_f32_16x16x32_bf16 v[78:81], v[168:171], v[192:195], v[78:81]
	v_mfma_f32_16x16x32_bf16 v[70:73], v[160:163], v[210:213], v[70:73]
	v_mfma_f32_16x16x32_bf16 v[66:69], v[168:171], v[210:213], v[66:69]
	s_setprio 0
	s_barrier
	s_add_i32 s20, s80, s42
	v_lshl_add_u64 v[196:197], s[30:31], 0, v[0:1]
	s_mov_b32 m0, s20
	ds_read_b128 v[172:175], v155 offset:16384
	ds_read_b128 v[176:179], v155 offset:17408
	ds_read_b128 v[180:183], v155 offset:18432
	ds_read_b128 v[184:187], v155 offset:19456
	ds_read_b128 v[188:191], v155 offset:20480
	ds_read_b128 v[192:195], v155 offset:21504
	ds_read_b128 v[206:209], v155 offset:22528
	ds_read_b128 v[210:213], v155 offset:23552
	global_load_lds_dwordx4 v[196:197], off
	s_add_i32 m0, s20, 0x2000
	s_add_u32 s20, s30, 0x40000
	v_lshl_add_u64 v[214:215], s[30:31], 0, v[142:143]
	s_addc_u32 s21, s31, 0
	s_add_i32 s80, s81, s42
	global_load_lds_dwordx4 v[214:215], off
	v_lshl_add_u64 v[216:217], s[20:21], 0, v[0:1]
	s_mov_b32 m0, s80
	v_lshl_add_u64 v[218:219], s[34:35], 0, v[142:143]
	global_load_lds_dwordx4 v[216:217], off
	s_add_i32 m0, s80, 0x2000
	v_lshl_add_u64 v[216:217], s[20:21], 0, v[142:143]
	global_load_lds_dwordx4 v[216:217], off
	s_mov_b32 m0, s43
	v_lshl_add_u64 v[216:217], s[34:35], 0, v[0:1]
	global_load_lds_dwordx4 v[216:217], off
	s_mov_b32 m0, s46
	s_nop 0
	global_load_lds_dwordx4 v[218:219], off
	s_waitcnt vmcnt(8)
	s_waitcnt lgkmcnt(0)
	s_barrier
; #define PG8_STAGE(bufoff, gbase, voff) do { _Pragma("unroll") for (int _i = 0; _i < 2; ++_i) \
;         __builtin_amdgcn_global_load_lds((const unsigned*)((const char*)(gbase) + (voff)[_i]), (PG8_LAS unsigned*)(lds + (bufoff) + ldsw + _i * 8192), 16, 0, 0); } while (0)
; #define PG8_LDA(dst, b, h) do { _Pragma("unroll") for (int m = 0; m < 4; ++m) _Pragma("unroll") for (int k = 0; k < 2; ++k) dst[m][k] = *(const PG8_LAS bf16x8*)(lds + PG8_SA(b, h) + aoff + m * 2048 + k * 1024); } while (0)
; #define PG8_LDB(dst, b, h) do { _Pragma("unroll") for (int n = 0; n < 2; ++n) _Pragma("unroll") for (int k = 0; k < 2; ++k) dst[n][k] = *(const PG8_LAS bf16x8*)(lds + PG8_SB(b, h) + boff + n * 2048 + k * 1024); } while (0)
; #define PG8_MMA(ai, bj, At, Bt) do { __builtin_amdgcn_s_setprio(1); _Pragma("unroll") for (int m = 0; m < 4; ++m) _Pragma("unroll") for (int n = 0; n < 2; ++n) _Pragma("unroll") for (int k = 0; k < 2; ++k) \
;         acc[ai][bj][m][n] = __builtin_amdgcn_mfma_f32_16x16x32_bf16(Bt[n][k], At[m][k], acc[ai][bj][m][n], 0, 0, 0); __builtin_amdgcn_s_setprio(0); } while (0)
; #define PG8_WAIT_V(n) asm volatile("s_waitcnt vmcnt(" #n ")" ::: "memory")
; #define PG8_WAIT_L(n) asm volatile("s_waitcnt lgkmcnt(" #n ")" ::: "memory")
; #define PG8_BAR __builtin_amdgcn_s_barrier()
; #define PG8_SCHED __builtin_amdgcn_sched_barrier(0)
; template <class Epi, class Sched, bool ALIGN_EPI = false, bool SP2 = false>
; __device__ __forceinline__ void gemm_phase(PG8_LAS unsigned char* lds, const Gemm g, const Sched& S, const Epi& E) {
;     ...
;             PG8_WAIT_V(8); PG8_WAIT_L(0); PG8_BAR; PG8_MMA(1, 0, At, B0); PG8_MMA(1, 1, At, B1); PG8_BAR; PG8_SCHED;
;             PG8_LDB(B0, 1, 0); PG8_LDB(B1, 1, 1); PG8_SCHED; PG8_LDA(At, 1, 0); PG8_STAGE(PG8_SA(0, 1), a2 + hstep, voffA);
;             PG8_WAIT_V(8); PG8_WAIT_L(0); PG8_BAR; PG8_MMA(0, 0, At, B0); PG8_MMA(0, 1, At, B1); PG8_BAR; PG8_SCHED;
	s_setprio 1
	v_mfma_f32_16x16x32_bf16 v[62:65], v[130:133], v[172:175], v[62:65]
	v_mfma_f32_16x16x32_bf16 v[58:61], v[138:141], v[172:175], v[58:61]
	v_mfma_f32_16x16x32_bf16 v[54:57], v[130:133], v[180:183], v[54:57]
	v_mfma_f32_16x16x32_bf16 v[42:45], v[138:141], v[180:183], v[42:45]
	v_mfma_f32_16x16x32_bf16 v[38:41], v[130:133], v[188:191], v[38:41]
	v_mfma_f32_16x16x32_bf16 v[26:29], v[138:141], v[188:191], v[26:29]
	v_mfma_f32_16x16x32_bf16 v[18:21], v[130:133], v[206:209], v[18:21]
	v_mfma_f32_16x16x32_bf16 v[10:13], v[138:141], v[206:209], v[10:13]
	v_mfma_f32_16x16x32_bf16 v[62:65], v[134:137], v[176:179], v[62:65]
	v_mfma_f32_16x16x32_bf16 v[58:61], v[148:151], v[176:179], v[58:61]
	v_mfma_f32_16x16x32_bf16 v[54:57], v[134:137], v[184:187], v[54:57]
	v_mfma_f32_16x16x32_bf16 v[42:45], v[148:151], v[184:187], v[42:45]
	v_mfma_f32_16x16x32_bf16 v[38:41], v[134:137], v[192:195], v[38:41]
	v_mfma_f32_16x16x32_bf16 v[26:29], v[148:151], v[192:195], v[26:29]
	v_mfma_f32_16x16x32_bf16 v[18:21], v[134:137], v[210:213], v[18:21]
	v_mfma_f32_16x16x32_bf16 v[10:13], v[148:151], v[210:213], v[10:13]
	v_mfma_f32_16x16x32_bf16 v[50:53], v[156:159], v[172:175], v[50:53]
	v_mfma_f32_16x16x32_bf16 v[46:49], v[164:167], v[172:175], v[46:49]
	v_mfma_f32_16x16x32_bf16 v[34:37], v[156:159], v[180:183], v[34:37]
	v_mfma_f32_16x16x32_bf16 v[30:33], v[164:167], v[180:183], v[30:33]
	v_mfma_f32_16x16x32_bf16 v[22:25], v[156:159], v[188:191], v[22:25]
	v_mfma_f32_16x16x32_bf16 v[14:17], v[164:167], v[188:191], v[14:17]
	v_mfma_f32_16x16x32_bf16 v[6:9], v[156:159], v[206:209], v[6:9]
	v_mfma_f32_16x16x32_bf16 v[2:5], v[164:167], v[206:209], v[2:5]
	v_mfma_f32_16x16x32_bf16 v[50:53], v[160:163], v[176:179], v[50:53]
	v_mfma_f32_16x16x32_bf16 v[46:49], v[168:171], v[176:179], v[46:49]
	v_mfma_f32_16x16x32_bf16 v[34:37], v[160:163], v[184:187], v[34:37]
	v_mfma_f32_16x16x32_bf16 v[30:33], v[168:171], v[184:187], v[30:33]
	v_mfma_f32_16x16x32_bf16 v[22:25], v[160:163], v[192:195], v[22:25]
	v_mfma_f32_16x16x32_bf16 v[14:17], v[168:171], v[192:195], v[14:17]
	v_mfma_f32_16x16x32_bf16 v[6:9], v[160:163], v[210:213], v[6:9]
	v_mfma_f32_16x16x32_bf16 v[2:5], v[168:171], v[210:213], v[2:5]
	s_setprio 0
	s_barrier
	s_add_i32 s80, 0, 0x18000
	s_add_i32 s81, 0, 0x1c000
	v_add_u32_e32 v148, s80, v153
	v_add_u32_e32 v168, s81, v153
	ds_read_b128 v[130:133], v148
	ds_read_b128 v[134:137], v148 offset:1024
	ds_read_b128 v[138:141], v148 offset:2048
	ds_read_b128 v[148:151], v148 offset:3072
	ds_read_b128 v[156:159], v168
	ds_read_b128 v[160:163], v168 offset:1024
	ds_read_b128 v[164:167], v168 offset:2048
	ds_read_b128 v[168:171], v168 offset:3072
	s_add_u32 s20, s34, 0x40000
	s_addc_u32 s21, s35, 0
	s_mov_b32 m0, s47
	v_lshl_add_u64 v[220:221], s[20:21], 0, v[0:1]
	ds_read_b128 v[172:175], v155 offset:32768
	ds_read_b128 v[176:179], v155 offset:33792
	ds_read_b128 v[180:183], v155 offset:34816
	ds_read_b128 v[184:187], v155 offset:35840
	ds_read_b128 v[188:191], v155 offset:36864
	ds_read_b128 v[192:195], v155 offset:37888
	ds_read_b128 v[206:209], v155 offset:38912
	ds_read_b128 v[210:213], v155 offset:39936
	global_load_lds_dwordx4 v[220:221], off
	s_mov_b32 m0, s52
	v_lshl_add_u64 v[220:221], s[20:21], 0, v[142:143]
	global_load_lds_dwordx4 v[220:221], off
	s_waitcnt vmcnt(8)
	s_waitcnt lgkmcnt(0)
	s_barrier
	s_setprio 1
	v_mfma_f32_16x16x32_bf16 v[126:129], v[130:133], v[172:175], v[126:129]
	v_mfma_f32_16x16x32_bf16 v[122:125], v[138:141], v[172:175], v[122:125]
	v_mfma_f32_16x16x32_bf16 v[118:121], v[130:133], v[180:183], v[118:121]
	v_mfma_f32_16x16x32_bf16 v[106:109], v[138:141], v[180:183], v[106:109]
	v_mfma_f32_16x16x32_bf16 v[102:105], v[130:133], v[188:191], v[102:105]
	v_mfma_f32_16x16x32_bf16 v[90:93], v[138:141], v[188:191], v[90:93]
	v_mfma_f32_16x16x32_bf16 v[86:89], v[130:133], v[206:209], v[86:89]
	v_mfma_f32_16x16x32_bf16 v[74:77], v[138:141], v[206:209], v[74:77]
	v_mfma_f32_16x16x32_bf16 v[126:129], v[134:137], v[176:179], v[126:129]
	v_mfma_f32_16x16x32_bf16 v[122:125], v[148:151], v[176:179], v[122:125]
	v_mfma_f32_16x16x32_bf16 v[118:121], v[134:137], v[184:187], v[118:121]
	v_mfma_f32_16x16x32_bf16 v[106:109], v[148:151], v[184:187], v[106:109]
	v_mfma_f32_16x16x32_bf16 v[102:105], v[134:137], v[192:195], v[102:105]
	v_mfma_f32_16x16x32_bf16 v[90:93], v[148:151], v[192:195], v[90:93]
	v_mfma_f32_16x16x32_bf16 v[86:89], v[134:137], v[210:213], v[86:89]
	v_mfma_f32_16x16x32_bf16 v[74:77], v[148:151], v[210:213], v[74:77]
	v_mfma_f32_16x16x32_bf16 v[114:117], v[156:159], v[172:175], v[114:117]
	v_mfma_f32_16x16x32_bf16 v[110:113], v[164:167], v[172:175], v[110:113]
	v_mfma_f32_16x16x32_bf16 v[98:101], v[156:159], v[180:183], v[98:101]
	v_mfma_f32_16x16x32_bf16 v[94:97], v[164:167], v[180:183], v[94:97]
	v_mfma_f32_16x16x32_bf16 v[82:85], v[156:159], v[188:191], v[82:85]
	v_mfma_f32_16x16x32_bf16 v[78:81], v[164:167], v[188:191], v[78:81]
	v_mfma_f32_16x16x32_bf16 v[70:73], v[156:159], v[206:209], v[70:73]
	v_mfma_f32_16x16x32_bf16 v[66:69], v[164:167], v[206:209], v[66:69]
	v_mfma_f32_16x16x32_bf16 v[114:117], v[160:163], v[176:179], v[114:117]
	v_mfma_f32_16x16x32_bf16 v[110:113], v[168:171], v[176:179], v[110:113]
	v_mfma_f32_16x16x32_bf16 v[98:101], v[160:163], v[184:187], v[98:101]
	v_mfma_f32_16x16x32_bf16 v[94:97], v[168:171], v[184:187], v[94:97]
	v_mfma_f32_16x16x32_bf16 v[82:85], v[160:163], v[192:195], v[82:85]
	v_mfma_f32_16x16x32_bf16 v[78:81], v[168:171], v[192:195], v[78:81]
	v_mfma_f32_16x16x32_bf16 v[70:73], v[160:163], v[210:213], v[70:73]
	v_mfma_f32_16x16x32_bf16 v[66:69], v[168:171], v[210:213], v[66:69]
	s_setprio 0
	s_barrier
; #define PG8_STAGE(bufoff, gbase, voff) do { _Pragma("unroll") for (int _i = 0; _i < 2; ++_i) \
;         __builtin_amdgcn_global_load_lds((const unsigned*)((const char*)(gbase) + (voff)[_i]), (PG8_LAS unsigned*)(lds + (bufoff) + ldsw + _i * 8192), 16, 0, 0); } while (0)
; #define PG8_LDA(dst, b, h) do { _Pragma("unroll") for (int m = 0; m < 4; ++m) _Pragma("unroll") for (int k = 0; k < 2; ++k) dst[m][k] = *(const PG8_LAS bf16x8*)(lds + PG8_SA(b, h) + aoff + m * 2048 + k * 1024); } while (0)
; #define PG8_MMA(ai, bj, At, Bt) do { __builtin_amdgcn_s_setprio(1); _Pragma("unroll") for (int m = 0; m < 4; ++m) _Pragma("unroll") for (int n = 0; n < 2; ++n) _Pragma("unroll") for (int k = 0; k < 2; ++k) \
;         acc[ai][bj][m][n] = __builtin_amdgcn_mfma_f32_16x16x32_bf16(Bt[n][k], At[m][k], acc[ai][bj][m][n], 0, 0, 0); __builtin_amdgcn_s_setprio(0); } while (0)
; #define PG8_WAIT_V(n) asm volatile("s_waitcnt vmcnt(" #n ")" ::: "memory")
; #define PG8_WAIT_L(n) asm volatile("s_waitcnt lgkmcnt(" #n ")" ::: "memory")
; #define PG8_BAR __builtin_amdgcn_s_barrier()
; #define PG8_SCHED __builtin_amdgcn_sched_barrier(0)
; template <class Epi, class Sched, bool ALIGN_EPI = false, bool SP2 = false>
; __device__ __forceinline__ void gemm_phase(PG8_LAS unsigned char* lds, const Gemm g, const Sched& S, const Epi& E) {
;     ...
;         for (int t = 0; t < nt; t += 2) {
;             const bool last = (t == nt - 2);
;             const char* a1 = cA + (size_t)(t + 1) * kstep;
;             const char* a2 = last ? nA : cA + (size_t)(t + 2) * kstep; const char* b2 = last ? nB : cB + (size_t)(t + 2) * kstep;
;     ...
;             PG8_LDA(At, 1, 1); PG8_STAGE(PG8_SB(1, 0), b3, voffB); PG8_STAGE(PG8_SB(1, 1), b3 + hstep, voffB); PG8_STAGE(PG8_SA(1, 0), a3, voffA);
;             PG8_WAIT_V(8); PG8_WAIT_L(0); PG8_BAR; PG8_MMA(1, 0, At, B0); PG8_MMA(1, 1, At, B1); PG8_BAR; PG8_SCHED;
	s_add_i32 s20, s80, s42
	v_lshl_add_u64 v[196:197], v[196:197], 0, s[24:25]
	s_mov_b32 m0, s20
	ds_read_b128 v[172:175], v155 offset:49152
	ds_read_b128 v[176:179], v155 offset:50176
	ds_read_b128 v[180:183], v155 offset:51200
	ds_read_b128 v[184:187], v155 offset:52224
	ds_read_b128 v[188:191], v155 offset:53248
	ds_read_b128 v[192:195], v155 offset:54272
	ds_read_b128 v[206:209], v155 offset:55296
	ds_read_b128 v[210:213], v155 offset:56320
	global_load_lds_dwordx4 v[196:197], off
	s_add_i32 m0, s20, 0x2000
	s_add_u32 s20, s30, 0x40080
	v_lshl_add_u64 v[196:197], v[214:215], 0, s[24:25]
	s_addc_u32 s21, s31, 0
	s_add_i32 s30, s81, s42
	global_load_lds_dwordx4 v[196:197], off
	s_mov_b32 m0, s30
	v_lshl_add_u64 v[196:197], s[20:21], 0, v[0:1]
	global_load_lds_dwordx4 v[196:197], off
	s_add_i32 m0, s30, 0x2000
	v_lshl_add_u64 v[196:197], s[20:21], 0, v[142:143]
	global_load_lds_dwordx4 v[196:197], off
	s_mov_b32 m0, s53
	v_lshl_add_u64 v[196:197], v[216:217], 0, s[24:25]
	global_load_lds_dwordx4 v[196:197], off
	s_mov_b32 m0, s55
	v_lshl_add_u64 v[196:197], v[218:219], 0, s[24:25]
	global_load_lds_dwordx4 v[196:197], off
	s_waitcnt vmcnt(8)
	s_waitcnt lgkmcnt(0)
	s_barrier
	s_setprio 1
	v_mfma_f32_16x16x32_bf16 v[62:65], v[130:133], v[172:175], v[62:65]
	v_mfma_f32_16x16x32_bf16 v[58:61], v[138:141], v[172:175], v[58:61]
	v_mfma_f32_16x16x32_bf16 v[54:57], v[130:133], v[180:183], v[54:57]
	v_mfma_f32_16x16x32_bf16 v[42:45], v[138:141], v[180:183], v[42:45]
	v_mfma_f32_16x16x32_bf16 v[38:41], v[130:133], v[188:191], v[38:41]
	v_mfma_f32_16x16x32_bf16 v[26:29], v[138:141], v[188:191], v[26:29]
	v_mfma_f32_16x16x32_bf16 v[18:21], v[130:133], v[206:209], v[18:21]
	v_mfma_f32_16x16x32_bf16 v[10:13], v[138:141], v[206:209], v[10:13]
	v_mfma_f32_16x16x32_bf16 v[62:65], v[134:137], v[176:179], v[62:65]
	v_mfma_f32_16x16x32_bf16 v[58:61], v[148:151], v[176:179], v[58:61]
	v_mfma_f32_16x16x32_bf16 v[54:57], v[134:137], v[184:187], v[54:57]
	v_mfma_f32_16x16x32_bf16 v[42:45], v[148:151], v[184:187], v[42:45]
	v_mfma_f32_16x16x32_bf16 v[38:41], v[134:137], v[192:195], v[38:41]
	v_mfma_f32_16x16x32_bf16 v[26:29], v[148:151], v[192:195], v[26:29]
	v_mfma_f32_16x16x32_bf16 v[18:21], v[134:137], v[210:213], v[18:21]
	v_mfma_f32_16x16x32_bf16 v[10:13], v[148:151], v[210:213], v[10:13]
	v_mfma_f32_16x16x32_bf16 v[50:53], v[156:159], v[172:175], v[50:53]
	v_mfma_f32_16x16x32_bf16 v[46:49], v[164:167], v[172:175], v[46:49]
	v_mfma_f32_16x16x32_bf16 v[34:37], v[156:159], v[180:183], v[34:37]
	v_mfma_f32_16x16x32_bf16 v[30:33], v[164:167], v[180:183], v[30:33]
	v_mfma_f32_16x16x32_bf16 v[22:25], v[156:159], v[188:191], v[22:25]
	v_mfma_f32_16x16x32_bf16 v[14:17], v[164:167], v[188:191], v[14:17]
	v_mfma_f32_16x16x32_bf16 v[6:9], v[156:159], v[206:209], v[6:9]
	v_mfma_f32_16x16x32_bf16 v[2:5], v[164:167], v[206:209], v[2:5]
	v_mfma_f32_16x16x32_bf16 v[50:53], v[160:163], v[176:179], v[50:53]
	v_mfma_f32_16x16x32_bf16 v[46:49], v[168:171], v[176:179], v[46:49]
	v_mfma_f32_16x16x32_bf16 v[34:37], v[160:163], v[184:187], v[34:37]
	v_mfma_f32_16x16x32_bf16 v[30:33], v[168:171], v[184:187], v[30:33]
	v_mfma_f32_16x16x32_bf16 v[22:25], v[160:163], v[192:195], v[22:25]
	v_mfma_f32_16x16x32_bf16 v[14:17], v[168:171], v[192:195], v[14:17]
	v_mfma_f32_16x16x32_bf16 v[6:9], v[160:163], v[210:213], v[6:9]
	v_mfma_f32_16x16x32_bf16 v[2:5], v[168:171], v[210:213], v[2:5]
	s_setprio 0
	s_barrier
	s_add_i32 s73, s73, 2
	s_add_u32 s8, s8, 0x100
	s_addc_u32 s9, s9, 0
	s_add_u32 s58, s58, 0x100
	s_addc_u32 s72, s72, 0
	s_cmp_gt_u32 s73, 13
	s_cbranch_scc0 .LBB0_351
	s_and_b64 vcc, exec, s[10:11]
	s_cbranch_vccz .LBB0_354
	s_barrier
